# v33 + combine row loop: the 12 next-row register copies and their counted waits deferred to the end of the row (one wait; removed slots kept as s_nop for result-use wait states)
# baseline (speedup 1.0000x reference)
.LBB0_326:
	s_or_b64 exec, exec, s[8:9]
	v_lshlrev_b32_e32 v74, 16, v64
	v_and_b32_e32 v75, 0xffff0000, v64
	v_lshlrev_b32_e32 v76, 16, v66
	v_and_b32_e32 v77, 0xffff0000, v66
	v_lshlrev_b32_e32 v64, 16, v65
	v_and_b32_e32 v65, 0xffff0000, v65
	v_lshlrev_b32_e32 v66, 16, v67
	v_and_b32_e32 v67, 0xffff0000, v67
	v_pk_add_f32 v[74:75], v[76:77], v[74:75]
	v_pk_add_f32 v[64:65], v[66:67], v[64:65]
	v_mov_b32_e32 v76, v75
	v_mov_b32_e32 v77, v65
	v_mov_b32_e32 v66, v74
	v_mov_b32_e32 v67, v64
	v_pk_mul_f32 v[76:77], v[76:77], v[76:77]
	s_mov_b32 s0, 0x3e85000
	v_pk_fma_f32 v[66:67], v[66:67], v[66:67], v[76:77]
	s_nop 0
	v_add_f32_e32 v66, v66, v67
	s_nop 1
	v_add_f32_dpp v66, v66, v66 quad_perm:[1,0,3,2] row_mask:0xf bank_mask:0xf bound_ctrl:1
	s_nop 1
	v_add_f32_dpp v66, v66, v66 quad_perm:[2,3,0,1] row_mask:0xf bank_mask:0xf bound_ctrl:1
	s_nop 1
	v_add_f32_dpp v66, v66, v66 row_half_mirror row_mask:0xf bank_mask:0xf bound_ctrl:1
	s_nop 1
	v_add_f32_dpp v66, v66, v66 row_mirror row_mask:0xf bank_mask:0xf bound_ctrl:1
	v_fmamk_f32 v66, v66, 0x3c800000, v237
	v_rsq_f32_e32 v66, v66
	s_nop 0
	v_pk_mul_f32 v[74:75], v[74:75], v[66:67] op_sel_hi:[1,0]
	v_pk_mul_f32 v[64:65], v[64:65], v[66:67] op_sel_hi:[1,0]
	v_pk_mul_f32 v[66:67], v[4:5], v[74:75]
	v_lshlrev_b32_e32 v74, 16, v62
	v_and_b32_e32 v75, 0xffff0000, v62
	v_mul_f32_e32 v62, 0xbfb8aa3b, v74
	v_exp_f32_e32 v62, v62
	v_pk_mul_f32 v[64:65], v[6:7], v[64:65]
	v_add_f32_e32 v62, 1.0, v62
	v_rcp_f32_e32 v76, v62
	v_mul_f32_e32 v62, 0xbfb8aa3b, v75
	v_exp_f32_e32 v62, v62
	s_nop 0
	v_add_f32_e32 v62, 1.0, v62
	v_rcp_f32_e32 v77, v62
	v_lshlrev_b32_e32 v62, 16, v63
	v_and_b32_e32 v63, 0xffff0000, v63
	v_pk_mul_f32 v[74:75], v[76:77], v[74:75]
	s_nop 0
	v_pk_mul_f32 v[66:67], v[74:75], v[66:67]
	s_nop 0
	v_cvt_pk_bf16_f32 v66, v66, v67
	v_mul_f32_e32 v67, 0xbfb8aa3b, v62
	v_exp_f32_e32 v67, v67
	s_nop 0
	v_add_f32_e32 v67, 1.0, v67
	v_rcp_f32_e32 v74, v67
	v_mul_f32_e32 v67, 0xbfb8aa3b, v63
	v_exp_f32_e32 v67, v67
	s_nop 0
	v_add_f32_e32 v67, 1.0, v67
	v_rcp_f32_e32 v75, v67
	s_nop 0
	v_pk_mul_f32 v[62:63], v[74:75], v[62:63]
	s_nop 0
	v_pk_mul_f32 v[62:63], v[62:63], v[64:65]
	v_lshlrev_b32_e32 v64, 16, v60
	v_cvt_pk_bf16_f32 v67, v62, v63
	v_add_co_u32_e32 v62, vcc, s0, v70
	v_and_b32_e32 v65, 0xffff0000, v60
	s_nop 0
	v_addc_co_u32_e32 v63, vcc, 0, v71, vcc
	global_store_dwordx2 v[62:63], v[66:67], off
	v_lshlrev_b32_e32 v66, 16, v58
	v_and_b32_e32 v67, 0xffff0000, v58
	v_lshlrev_b32_e32 v60, 16, v61
	v_and_b32_e32 v61, 0xffff0000, v61
	v_lshlrev_b32_e32 v58, 16, v59
	v_and_b32_e32 v59, 0xffff0000, v59
	v_pk_add_f32 v[64:65], v[66:67], v[64:65]
	v_pk_add_f32 v[58:59], v[58:59], v[60:61]
	v_mov_b32_e32 v66, v65
	v_mov_b32_e32 v67, v59
	v_mov_b32_e32 v60, v64
	v_mov_b32_e32 v61, v58
	v_pk_mul_f32 v[66:67], v[66:67], v[66:67]
	s_mov_b64 s[0:1], 0x800
	v_pk_fma_f32 v[60:61], v[60:61], v[60:61], v[66:67]
	v_lshl_add_u64 v[20:21], v[20:21], 0, s[0:1]
	v_add_f32_e32 v60, v60, v61
	s_mov_b64 s[0:1], 0x1c00
	v_lshl_add_u64 v[24:25], v[24:25], 0, s[0:1]
	v_add_f32_dpp v60, v60, v60 quad_perm:[1,0,3,2] row_mask:0xf bank_mask:0xf bound_ctrl:1
	s_nop 1
	v_add_f32_dpp v60, v60, v60 quad_perm:[2,3,0,1] row_mask:0xf bank_mask:0xf bound_ctrl:1
	s_nop 1
	v_add_f32_dpp v60, v60, v60 row_half_mirror row_mask:0xf bank_mask:0xf bound_ctrl:1
	s_nop 1
	v_add_f32_dpp v60, v60, v60 row_mirror row_mask:0xf bank_mask:0xf bound_ctrl:1
	v_fmamk_f32 v60, v60, 0x3c800000, v237
	v_rsq_f32_e32 v60, v60
	s_nop 0
	v_pk_mul_f32 v[58:59], v[58:59], v[60:61] op_sel_hi:[1,0]
	v_pk_mul_f32 v[60:61], v[64:65], v[60:61] op_sel_hi:[1,0]
	v_lshlrev_b32_e32 v64, 16, v56
	v_and_b32_e32 v65, 0xffff0000, v56
	v_mul_f32_e32 v56, 0xbfb8aa3b, v64
	v_exp_f32_e32 v56, v56
	s_nop 0
	v_add_f32_e32 v56, 1.0, v56
	v_rcp_f32_e32 v66, v56
	v_mul_f32_e32 v56, 0xbfb8aa3b, v65
	v_exp_f32_e32 v56, v56
	s_nop 0
	v_add_f32_e32 v56, 1.0, v56
	v_rcp_f32_e32 v67, v56
	s_nop 0
	v_pk_mul_f32 v[64:65], v[66:67], v[64:65]
	s_nop 0
	v_pk_mul_f32 v[60:61], v[64:65], v[60:61]
	s_nop 0
	s_nop 0
	v_cvt_pk_bf16_f32 v56, v60, v61
	v_lshlrev_b32_e32 v60, 16, v57
	v_and_b32_e32 v61, 0xffff0000, v57
	v_mul_f32_e32 v57, 0xbfb8aa3b, v60
	v_exp_f32_e32 v57, v57
	s_nop 0
	v_add_f32_e32 v57, 1.0, v57
	v_rcp_f32_e32 v64, v57
	v_mul_f32_e32 v57, 0xbfb8aa3b, v61
	v_exp_f32_e32 v57, v57
	s_nop 0
	v_add_f32_e32 v57, 1.0, v57
	v_rcp_f32_e32 v65, v57
	s_nop 0
	v_pk_mul_f32 v[60:61], v[64:65], v[60:61]
	s_nop 0
	v_pk_mul_f32 v[58:59], v[60:61], v[58:59]
	s_nop 0
	v_cvt_pk_bf16_f32 v57, v58, v59
	global_store_dwordx2 v[62:63], v[56:57], off offset:512
	v_lshlrev_b32_e32 v56, 16, v54
	v_and_b32_e32 v57, 0xffff0000, v54
	v_lshlrev_b32_e32 v58, 16, v52
	v_and_b32_e32 v59, 0xffff0000, v52
	v_lshlrev_b32_e32 v54, 16, v55
	v_and_b32_e32 v55, 0xffff0000, v55
	v_lshlrev_b32_e32 v52, 16, v53
	v_and_b32_e32 v53, 0xffff0000, v53
	v_pk_add_f32 v[56:57], v[58:59], v[56:57]
	v_pk_add_f32 v[52:53], v[52:53], v[54:55]
	v_mov_b32_e32 v58, v57
	v_mov_b32_e32 v59, v53
	v_mov_b32_e32 v54, v56
	v_mov_b32_e32 v55, v52
	v_pk_mul_f32 v[58:59], v[58:59], v[58:59]
	s_nop 0
	v_pk_fma_f32 v[54:55], v[54:55], v[54:55], v[58:59]
	s_nop 0
	v_add_f32_e32 v54, v54, v55
	s_nop 1
	v_add_f32_dpp v54, v54, v54 quad_perm:[1,0,3,2] row_mask:0xf bank_mask:0xf bound_ctrl:1
	s_nop 1
	v_add_f32_dpp v54, v54, v54 quad_perm:[2,3,0,1] row_mask:0xf bank_mask:0xf bound_ctrl:1
	s_nop 1
	v_add_f32_dpp v54, v54, v54 row_half_mirror row_mask:0xf bank_mask:0xf bound_ctrl:1
	s_nop 1
	v_add_f32_dpp v54, v54, v54 row_mirror row_mask:0xf bank_mask:0xf bound_ctrl:1
	v_fmamk_f32 v54, v54, 0x3c800000, v237
	v_rsq_f32_e32 v54, v54
	s_nop 0
	v_pk_mul_f32 v[56:57], v[56:57], v[54:55] op_sel_hi:[1,0]
	v_pk_mul_f32 v[52:53], v[52:53], v[54:55] op_sel_hi:[1,0]
	v_pk_mul_f32 v[54:55], v[8:9], v[56:57]
	v_lshlrev_b32_e32 v56, 16, v50
	v_and_b32_e32 v57, 0xffff0000, v50
	v_mul_f32_e32 v50, 0xbfb8aa3b, v56
	v_exp_f32_e32 v50, v50
	v_pk_mul_f32 v[52:53], v[10:11], v[52:53]
	v_add_f32_e32 v50, 1.0, v50
	v_rcp_f32_e32 v58, v50
	v_mul_f32_e32 v50, 0xbfb8aa3b, v57
	v_exp_f32_e32 v50, v50
	s_nop 0
	v_add_f32_e32 v50, 1.0, v50
	v_rcp_f32_e32 v59, v50
	s_nop 0
	v_pk_mul_f32 v[56:57], v[58:59], v[56:57]
	s_nop 0
	v_pk_mul_f32 v[54:55], v[56:57], v[54:55]
	s_nop 0
	s_nop 0
	v_cvt_pk_bf16_f32 v50, v54, v55
	v_lshlrev_b32_e32 v54, 16, v51
	v_and_b32_e32 v55, 0xffff0000, v51
	v_mul_f32_e32 v51, 0xbfb8aa3b, v54
	v_exp_f32_e32 v51, v51
	s_nop 0
	v_add_f32_e32 v51, 1.0, v51
	v_rcp_f32_e32 v56, v51
	v_mul_f32_e32 v51, 0xbfb8aa3b, v55
	v_exp_f32_e32 v51, v51
	s_nop 0
	v_add_f32_e32 v51, 1.0, v51
	v_rcp_f32_e32 v57, v51
	s_nop 0
	v_pk_mul_f32 v[54:55], v[56:57], v[54:55]
	s_nop 0
	v_pk_mul_f32 v[52:53], v[54:55], v[52:53]
	s_nop 0
	s_nop 0
	v_cvt_pk_bf16_f32 v51, v52, v53
	global_store_dwordx2 v[62:63], v[50:51], off offset:1024
	v_lshlrev_b32_e32 v50, 16, v18
	v_and_b32_e32 v51, 0xffff0000, v18
	v_lshlrev_b32_e32 v52, 16, v16
	v_and_b32_e32 v53, 0xffff0000, v16
	v_pk_add_f32 v[50:51], v[52:53], v[50:51]
	v_lshlrev_b32_e32 v52, 16, v22
	v_and_b32_e32 v53, 0xffff0000, v22
	v_pk_fma_f32 v[50:51], v[12:13], v[52:53], v[50:51]
	v_lshlrev_b32_e32 v18, 16, v19
	v_mul_f32_e32 v16, 0x3d372713, v50
	v_mul_f32_e32 v16, v50, v16
	v_fma_f32 v16, v50, v16, v50
	v_mul_f32_e32 v16, 0x3f4c422a, v16
	v_mul_f32_e32 v16, 0xc038aa3b, v16
	v_exp_f32_e32 v16, v16
	v_and_b32_e32 v19, 0xffff0000, v19
	v_lshlrev_b32_e32 v22, 16, v23
	v_and_b32_e32 v23, 0xffff0000, v23
	v_add_f32_e32 v16, 1.0, v16
	v_rcp_f32_e32 v52, v16
	v_mul_f32_e32 v16, 0x3d372713, v51
	v_mul_f32_e32 v16, v51, v16
	v_fma_f32 v16, v51, v16, v51
	v_mul_f32_e32 v16, 0x3f4c422a, v16
	v_mul_f32_e32 v16, 0xc038aa3b, v16
	v_exp_f32_e32 v16, v16
	s_nop 0
	v_add_f32_e32 v16, 1.0, v16
	v_rcp_f32_e32 v53, v16
	s_nop 0
	v_pk_mul_f32 v[50:51], v[50:51], v[52:53]
	s_nop 0
	v_cvt_pk_bf16_f32 v16, v50, v51
	v_lshlrev_b32_e32 v50, 16, v17
	v_and_b32_e32 v51, 0xffff0000, v17
	v_pk_add_f32 v[18:19], v[50:51], v[18:19]
	s_nop 0
	s_nop 0
	v_pk_fma_f32 v[18:19], v[14:15], v[22:23], v[18:19]
	s_nop 0
	v_mul_f32_e32 v17, 0x3d372713, v18
	v_mul_f32_e32 v17, v18, v17
	v_fma_f32 v17, v18, v17, v18
	v_mul_f32_e32 v17, 0x3f4c422a, v17
	v_mul_f32_e32 v17, 0xc038aa3b, v17
	v_exp_f32_e32 v17, v17
	s_nop 0
	v_add_f32_e32 v17, 1.0, v17
	v_rcp_f32_e32 v22, v17
	v_mul_f32_e32 v17, 0x3d372713, v19
	v_mul_f32_e32 v17, v19, v17
	v_fma_f32 v17, v19, v17, v19
	v_mul_f32_e32 v17, 0x3f4c422a, v17
	v_mul_f32_e32 v17, 0xc038aa3b, v17
	v_exp_f32_e32 v17, v17
	s_nop 0
	v_add_f32_e32 v17, 1.0, v17
	v_rcp_f32_e32 v23, v17
	s_nop 0
	v_pk_mul_f32 v[18:19], v[18:19], v[22:23]
	s_nop 0
	v_cvt_pk_bf16_f32 v17, v18, v19
	global_store_dwordx2 v[62:63], v[16:17], off offset:1536
	s_nop 0
	s_nop 0
	s_nop 0
	s_nop 0
	s_nop 0
	s_waitcnt vmcnt(4)
	v_mov_b64_e32 v[66:67], v[26:27]
	v_mov_b64_e32 v[64:65], v[32:33]
	v_mov_b64_e32 v[60:61], v[38:39]
	v_mov_b64_e32 v[58:59], v[40:41]
	v_mov_b64_e32 v[56:57], v[30:31]
	v_mov_b64_e32 v[54:55], v[44:45]
	v_mov_b64_e32 v[50:51], v[34:35]
	v_mov_b64_e32 v[52:53], v[42:43]
	v_mov_b64_e32 v[62:63], v[28:29]
	v_mov_b64_e32 v[22:23], v[36:37]
	v_mov_b64_e32 v[16:17], v[46:47]
	v_mov_b64_e32 v[18:19], v[48:49]
	s_andn2_b64 exec, exec, s[12:13]
	s_cbranch_execz .LBB0_329
